# summary tile carry blocks: seven per-result LDS waits coalesced into three (4/2/0)
# speedup vs baseline: 1.0016x; 1.0016x over previous
.Lsl_skip1:
	v_exp_f32_e32 v103, v219
	v_exp_f32_e32 v108, v222
	v_exp_f32_e32 v109, v223
	v_rcp_f32_e32 v98, v98
	v_rcp_f32_e32 v99, v99
	v_sqrt_f32_e32 v100, v100
	v_sqrt_f32_e32 v101, v101
	v_exp_f32_e32 v106, v206
	v_exp_f32_e32 v107, v207
	v_pk_add_f32 v[102:103], v[102:103], 1.0 op_sel_hi:[1,0]
	v_pk_add_f32 v[108:109], v[108:109], 1.0 op_sel_hi:[1,0]
	v_rcp_f32_e32 v102, v102
	v_rcp_f32_e32 v103, v103
	v_pk_mul_f32 v[98:99], v[98:99], v[126:127]
	v_rcp_f32_e32 v108, v108
	v_rcp_f32_e32 v109, v109
	v_pk_mul_f32 v[98:99], v[98:99], v[100:101]
	v_pk_add_f32 v[100:101], v[106:107], 1.0 op_sel_hi:[1,0]
	v_pk_fma_f32 v[106:107], v[110:111], v[110:111], 1.0 op_sel_hi:[1,1,0] neg_lo:[1,0,0] neg_hi:[1,0,0] clamp
	v_rcp_f32_e32 v100, v100
	v_rcp_f32_e32 v101, v101
	v_sqrt_f32_e32 v106, v106
	v_pk_mul_f32 v[102:103], v[102:103], v[6:7] op_sel_hi:[1,0]
	v_sqrt_f32_e32 v107, v107
	v_exp_f32_e32 v128, v102
	v_exp_f32_e32 v129, v103
	v_pk_mul_f32 v[102:103], v[108:109], v[124:125]
	v_exp_f32_e32 v108, v220
	v_exp_f32_e32 v109, v221
	v_pk_mul_f32 v[100:101], v[100:101], v[122:123]
	v_exp_f32_e32 v204, v230
	v_pk_mul_f32 v[100:101], v[100:101], v[106:107]
	v_pk_fma_f32 v[106:107], v[128:129], v[128:129], 1.0 op_sel_hi:[1,1,0] neg_lo:[1,0,0] neg_hi:[1,0,0] clamp
	v_pk_add_f32 v[108:109], v[108:109], 1.0 op_sel_hi:[1,0]
	v_exp_f32_e32 v205, v231
	v_rcp_f32_e32 v108, v108
	v_rcp_f32_e32 v109, v109
	v_sqrt_f32_e32 v106, v106
	v_sqrt_f32_e32 v107, v107
	v_pk_add_f32 v[204:205], v[204:205], 1.0 op_sel_hi:[1,0]
	v_pk_mul_f32 v[108:109], v[108:109], v[6:7] op_sel_hi:[1,0]
	v_rcp_f32_e32 v204, v204
	v_rcp_f32_e32 v205, v205
	v_exp_f32_e32 v130, v108
	v_exp_f32_e32 v131, v109
	v_pk_mul_f32 v[102:103], v[102:103], v[106:107]
	v_exp_f32_e32 v106, v224
	v_exp_f32_e32 v107, v225
	v_pk_mul_f32 v[204:205], v[6:7], v[204:205] op_sel_hi:[0,1]
	v_pk_fma_f32 v[108:109], v[130:131], v[130:131], 1.0 op_sel_hi:[1,1,0] neg_lo:[1,0,0] neg_hi:[1,0,0] clamp
	v_exp_f32_e32 v218, v204
	v_exp_f32_e32 v219, v205
	v_exp_f32_e32 v204, v232
	v_exp_f32_e32 v205, v233
	v_pk_add_f32 v[106:107], v[106:107], 1.0 op_sel_hi:[1,0]
	v_rcp_f32_e32 v106, v106
	v_rcp_f32_e32 v107, v107
	v_sqrt_f32_e32 v108, v108
	v_sqrt_f32_e32 v109, v109
	v_exp_f32_e32 v206, v226
	v_exp_f32_e32 v207, v227
	v_pk_add_f32 v[204:205], v[204:205], 1.0 op_sel_hi:[1,0]
	v_pk_mul_f32 v[106:107], v[106:107], v[120:121]
	v_rcp_f32_e32 v204, v204
	v_rcp_f32_e32 v205, v205
	v_pk_mul_f32 v[106:107], v[106:107], v[108:109]
	v_pk_add_f32 v[108:109], v[206:207], 1.0 op_sel_hi:[1,0]
	v_pk_fma_f32 v[206:207], v[218:219], v[218:219], 1.0 op_sel_hi:[1,1,0] neg_lo:[1,0,0] neg_hi:[1,0,0] clamp
	v_exp_f32_e32 v208, v228
	v_rcp_f32_e32 v108, v108
	v_rcp_f32_e32 v109, v109
	v_sqrt_f32_e32 v206, v206
	v_pk_mul_f32 v[204:205], v[6:7], v[204:205] op_sel_hi:[0,1]
	v_sqrt_f32_e32 v207, v207
	v_exp_f32_e32 v220, v204
	v_exp_f32_e32 v221, v205
	v_lshlrev_b32_e32 v119, 16, v17
	v_pk_add_f32 v[208:209], v[208:209], 1.0 op_sel_hi:[1,0]
	v_exp_f32_e32 v92, v92
	v_exp_f32_e32 v93, v93
	v_rcp_f32_e32 v208, v208
	v_rcp_f32_e32 v209, v209
	v_pk_mul_f32 v[108:109], v[108:109], v[118:119]
	v_exp_f32_e32 v94, v94
	v_pk_mul_f32 v[108:109], v[108:109], v[206:207]
	v_pk_fma_f32 v[206:207], v[220:221], v[220:221], 1.0 op_sel_hi:[1,1,0] neg_lo:[1,0,0] neg_hi:[1,0,0] clamp
	v_exp_f32_e32 v95, v95
	v_lshlrev_b32_e32 v116, 16, v19
	v_lshlrev_b32_e32 v117, 16, v154
	v_sqrt_f32_e32 v206, v206
	v_pk_add_f32 v[92:93], v[92:93], 1.0 op_sel_hi:[1,0]
	v_pk_mul_f32 v[204:205], v[208:209], v[116:117]
	v_sqrt_f32_e32 v207, v207
	v_rcp_f32_e32 v208, v92
	v_rcp_f32_e32 v209, v93
	v_pk_add_f32 v[94:95], v[94:95], 1.0 op_sel_hi:[1,0]
	v_pk_mul_f32 v[92:93], v[204:205], v[206:207]
	v_rcp_f32_e32 v94, v94
	v_rcp_f32_e32 v95, v95
	v_pk_mul_f32 v[204:205], v[6:7], v[208:209] op_sel_hi:[0,1]
	v_exp_f32_e32 v222, v204
	v_exp_f32_e32 v223, v205
	v_exp_f32_e32 v88, v88
	v_exp_f32_e32 v89, v89
	v_pk_mul_f32 v[6:7], v[6:7], v[94:95] op_sel_hi:[0,1]
	v_exp_f32_e32 v6, v6
	v_exp_f32_e32 v7, v7
	v_exp_f32_e32 v90, v90
	v_exp_f32_e32 v91, v91
	v_pk_fma_f32 v[204:205], v[222:223], v[222:223], 1.0 op_sel_hi:[1,1,0] neg_lo:[1,0,0] neg_hi:[1,0,0] clamp
	v_pk_add_f32 v[88:89], v[88:89], 1.0 op_sel_hi:[1,0]
	v_rcp_f32_e32 v88, v88
	v_rcp_f32_e32 v89, v89
	v_sqrt_f32_e32 v204, v204
	v_pk_fma_f32 v[94:95], v[6:7], v[6:7], 1.0 op_sel_hi:[1,1,0] neg_lo:[1,0,0] neg_hi:[1,0,0] clamp
	v_sqrt_f32_e32 v205, v205
	v_pk_add_f32 v[90:91], v[90:91], 1.0 op_sel_hi:[1,0]
	v_rcp_f32_e32 v90, v90
	v_rcp_f32_e32 v91, v91
	v_sqrt_f32_e32 v206, v94
	v_fma_f32 v98, 0, v96, v98
	v_lshlrev_b32_e32 v114, 16, v155
	v_lshlrev_b32_e32 v115, 16, v203
	v_sqrt_f32_e32 v207, v95
	v_fmac_f32_e32 v99, v97, v98
	v_mul_f32_e32 v97, v96, v97
	v_pk_mul_f32 v[88:89], v[88:89], v[114:115]
	v_mul_f32_e32 v203, v110, v97
	v_fma_f32 v100, v110, v99, v100
	v_pk_mul_f32 v[94:95], v[88:89], v[204:205]
	v_fmac_f32_e32 v101, v111, v100
	v_mul_f32_e32 v204, v111, v203
	v_pk_mul_f32 v[88:89], v[90:91], v[104:105]
	v_mul_f32_e32 v205, v128, v204
	v_fma_f32 v102, v128, v101, v102
	v_pk_mul_f32 v[88:89], v[88:89], v[206:207]
	v_fmac_f32_e32 v103, v129, v102
	v_mul_f32_e32 v207, v129, v205
	v_mul_f32_e32 v208, v130, v207
	v_fma_f32 v106, v130, v103, v106
	v_fmac_f32_e32 v107, v131, v106
	v_mul_f32_e32 v212, v131, v208
	v_mul_f32_e32 v206, v218, v212
	v_fma_f32 v108, v218, v107, v108
	v_fmac_f32_e32 v109, v219, v108
	v_mul_f32_e32 v209, v219, v206
	v_mul_f32_e32 v211, v220, v209
	v_fma_f32 v92, v220, v109, v92
	v_fmac_f32_e32 v93, v221, v92
	v_mul_f32_e32 v213, v221, v211
	v_mul_f32_e32 v217, v222, v213
	v_fma_f32 v94, v222, v93, v94
	v_fmac_f32_e32 v95, v223, v94
	v_mul_f32_e32 v218, v223, v217
	v_mul_f32_e32 v219, v6, v218
	v_fma_f32 v88, v6, v95, v88
	v_fmac_f32_e32 v89, v7, v88
	v_mul_f32_e32 v90, v7, v219
	ds_bpermute_b32 v110, v182, v90
	ds_bpermute_b32 v5, v182, v89
	ds_bpermute_b32 v111, v190, v90
	ds_bpermute_b32 v17, v190, v89
	ds_bpermute_b32 v130, v191, v90
	ds_bpermute_b32 v91, v191, v89
	ds_bpermute_b32 v131, v192, v90
	ds_bpermute_b32 v7, v192, v89
	v_ashrrev_i32_e32 v19, 31, v18
	v_lshl_add_u64 v[128:129], v[18:19], 3, s[28:29]
	s_and_saveexec_b64 s[34:35], s[40:41]
	s_cbranch_execz .LBB0_430
	s_waitcnt lgkmcnt(4)
	v_fmac_f32_e32 v5, 0, v110
	v_mul_f32_e32 v6, v110, v111
	v_fmac_f32_e32 v17, v5, v111
	s_waitcnt lgkmcnt(2)
	v_mul_f32_e32 v6, v6, v130
	v_fmac_f32_e32 v91, v17, v130
	s_waitcnt lgkmcnt(0)
	v_mul_f32_e32 v6, v6, v131
	v_fmac_f32_e32 v7, v91, v131
	global_store_dwordx2 v[128:129], v[6:7], off sc1

.Lsl_skip2:
	v_pk_mul_f32 v[0:1], v[0:1], v[148:149] op_sel_hi:[1,0]
	v_sqrt_f32_e32 v9, v21
	v_exp_f32_e32 v228, v0
	v_exp_f32_e32 v229, v1
	v_pk_add_f32 v[2:3], v[22:23], 1.0 op_sel_hi:[1,0]
	v_exp_f32_e32 v6, v230
	v_rcp_f32_e32 v2, v2
	v_pk_fma_f32 v[4:5], v[228:229], v[228:229], 1.0 op_sel_hi:[1,1,0] neg_lo:[1,0,0] neg_hi:[1,0,0] clamp
	v_rcp_f32_e32 v3, v3
	v_sqrt_f32_e32 v4, v4
	v_sqrt_f32_e32 v5, v5
	v_exp_f32_e32 v7, v231
	v_pk_mul_f32 v[0:1], v[236:237], v[122:123]
	v_pk_mul_f32 v[2:3], v[2:3], v[124:125]
	v_pk_mul_f32 v[0:1], v[0:1], v[8:9]
	v_exp_f32_e32 v8, v220
	v_exp_f32_e32 v9, v221
	v_pk_mul_f32 v[2:3], v[2:3], v[4:5]
	v_exp_f32_e32 v4, v234
	v_exp_f32_e32 v5, v235
	v_pk_add_f32 v[6:7], v[6:7], 1.0 op_sel_hi:[1,0]
	v_pk_add_f32 v[8:9], v[8:9], 1.0 op_sel_hi:[1,0]
	v_rcp_f32_e32 v6, v6
	v_rcp_f32_e32 v7, v7
	v_pk_add_f32 v[4:5], v[4:5], 1.0 op_sel_hi:[1,0]
	v_rcp_f32_e32 v8, v8
	v_rcp_f32_e32 v9, v9
	v_rcp_f32_e32 v4, v4
	v_rcp_f32_e32 v5, v5
	v_pk_mul_f32 v[6:7], v[6:7], v[148:149] op_sel_hi:[1,0]
	v_pk_mul_f32 v[8:9], v[148:149], v[8:9] op_sel_hi:[0,1]
	v_exp_f32_e32 v122, v6
	v_exp_f32_e32 v123, v7
	v_pk_mul_f32 v[4:5], v[4:5], v[120:121]
	v_exp_f32_e32 v120, v8
	v_exp_f32_e32 v121, v9
	v_exp_f32_e32 v8, v222
	v_exp_f32_e32 v9, v223
	v_pk_fma_f32 v[6:7], v[122:123], v[122:123], 1.0 op_sel_hi:[1,1,0] neg_lo:[1,0,0] neg_hi:[1,0,0] clamp
	v_exp_f32_e32 v18, v224
	v_sqrt_f32_e32 v6, v6
	v_sqrt_f32_e32 v7, v7
	v_exp_f32_e32 v19, v225
	v_pk_add_f32 v[8:9], v[8:9], 1.0 op_sel_hi:[1,0]
	v_exp_f32_e32 v20, v226
	v_rcp_f32_e32 v8, v8
	v_rcp_f32_e32 v9, v9
	v_exp_f32_e32 v21, v227
	v_pk_mul_f32 v[4:5], v[4:5], v[6:7]
	v_pk_add_f32 v[6:7], v[18:19], 1.0 op_sel_hi:[1,0]
	v_pk_fma_f32 v[18:19], v[120:121], v[120:121], 1.0 op_sel_hi:[1,1,0] neg_lo:[1,0,0] neg_hi:[1,0,0] clamp
	v_rcp_f32_e32 v6, v6
	v_rcp_f32_e32 v7, v7
	v_pk_mul_f32 v[8:9], v[148:149], v[8:9] op_sel_hi:[0,1]
	v_sqrt_f32_e32 v18, v18
	v_sqrt_f32_e32 v19, v19
	v_exp_f32_e32 v22, v8
	v_exp_f32_e32 v23, v9
	v_pk_add_f32 v[20:21], v[20:21], 1.0 op_sel_hi:[1,0]
	v_pk_mul_f32 v[6:7], v[6:7], v[118:119]
	v_rcp_f32_e32 v20, v20
	v_rcp_f32_e32 v21, v21
	v_pk_mul_f32 v[6:7], v[6:7], v[18:19]
	v_pk_fma_f32 v[18:19], v[22:23], v[22:23], 1.0 op_sel_hi:[1,1,0] neg_lo:[1,0,0] neg_hi:[1,0,0] clamp
	v_pk_add_f32 v[10:11], v[10:11], 1.0 op_sel_hi:[1,0]
	v_pk_mul_f32 v[8:9], v[20:21], v[116:117]
	v_sqrt_f32_e32 v18, v18
	v_sqrt_f32_e32 v19, v19
	v_rcp_f32_e32 v20, v10
	v_rcp_f32_e32 v21, v11
	v_pk_mul_f32 v[10:11], v[8:9], v[18:19]
	v_exp_f32_e32 v8, v14
	v_exp_f32_e32 v9, v15
	v_pk_mul_f32 v[14:15], v[148:149], v[20:21] op_sel_hi:[0,1]
	v_exp_f32_e32 v20, v14
	v_exp_f32_e32 v21, v15
	v_pk_add_f32 v[8:9], v[8:9], 1.0 op_sel_hi:[1,0]
	s_nop 0
	v_rcp_f32_e32 v14, v8
	v_rcp_f32_e32 v15, v9
	v_pk_fma_f32 v[8:9], v[20:21], v[20:21], 1.0 op_sel_hi:[1,1,0] neg_lo:[1,0,0] neg_hi:[1,0,0] clamp
	v_pk_mul_f32 v[14:15], v[14:15], v[114:115]
	v_sqrt_f32_e32 v18, v8
	v_sqrt_f32_e32 v19, v9
	v_pk_add_f32 v[8:9], v[12:13], 1.0 op_sel_hi:[1,0]
	v_exp_f32_e32 v12, v16
	v_rcp_f32_e32 v8, v8
	v_rcp_f32_e32 v9, v9
	v_exp_f32_e32 v13, v17
	v_pk_mul_f32 v[8:9], v[148:149], v[8:9] op_sel_hi:[0,1]
	v_exp_f32_e32 v8, v8
	v_exp_f32_e32 v9, v9
	v_pk_add_f32 v[12:13], v[12:13], 1.0 op_sel_hi:[1,0]
	v_pk_mul_f32 v[14:15], v[14:15], v[18:19]
	v_rcp_f32_e32 v12, v12
	v_pk_fma_f32 v[16:17], v[8:9], v[8:9], 1.0 op_sel_hi:[1,1,0] neg_lo:[1,0,0] neg_hi:[1,0,0] clamp
	v_rcp_f32_e32 v13, v13
	v_sqrt_f32_e32 v16, v16
	v_sqrt_f32_e32 v17, v17
	v_pk_mul_f32 v[12:13], v[12:13], v[104:105]
	s_nop 0
	v_pk_mul_f32 v[12:13], v[12:13], v[16:17]
	s_nop 0
	v_fma_f32 v13, 0, v9, v13
	v_fmac_f32_e32 v12, v8, v13
	v_mul_f32_e32 v8, v9, v8
	v_mul_f32_e32 v18, v21, v8
	v_fma_f32 v15, v21, v12, v15
	v_fmac_f32_e32 v14, v20, v15
	v_mul_f32_e32 v19, v20, v18
	v_mul_f32_e32 v20, v23, v19
	v_fma_f32 v11, v23, v14, v11
	v_fmac_f32_e32 v10, v22, v11
	v_mul_f32_e32 v21, v22, v20
	v_mul_f32_e32 v22, v121, v21
	v_fma_f32 v7, v121, v10, v7
	v_fmac_f32_e32 v6, v120, v7
	v_mul_f32_e32 v23, v120, v22
	v_mul_f32_e32 v104, v123, v23
	v_fma_f32 v5, v123, v6, v5
	v_fmac_f32_e32 v4, v122, v5
	v_mul_f32_e32 v105, v122, v104
	v_mul_f32_e32 v114, v229, v105
	v_fma_f32 v3, v229, v4, v3
	v_fmac_f32_e32 v2, v228, v3
	v_mul_f32_e32 v115, v228, v114
	v_mul_f32_e32 v116, v127, v115
	v_fma_f32 v1, v127, v2, v1
	v_fmac_f32_e32 v0, v126, v1
	v_mul_f32_e32 v117, v126, v116
	v_mul_f32_e32 v118, v131, v117
	v_fma_f32 v111, v131, v0, v111
	v_fmac_f32_e32 v110, v130, v111
	v_mul_f32_e32 v91, v130, v118
	ds_bpermute_b32 v122, v192, v91
	ds_bpermute_b32 v119, v192, v110
	ds_bpermute_b32 v123, v191, v91
	ds_bpermute_b32 v120, v191, v110
	ds_bpermute_b32 v124, v190, v91
	ds_bpermute_b32 v121, v190, v110
	ds_bpermute_b32 v125, v182, v91
	ds_bpermute_b32 v17, v182, v110
	s_and_saveexec_b64 s[34:35], s[40:41]
	s_cbranch_execz .LBB0_425
	s_waitcnt lgkmcnt(4)
	v_fmac_f32_e32 v119, 0, v122
	v_mul_f32_e32 v16, v122, v123
	v_fmac_f32_e32 v120, v119, v123
	s_waitcnt lgkmcnt(2)
	v_mul_f32_e32 v16, v16, v124
	v_fmac_f32_e32 v121, v120, v124
	v_add_co_u32_e32 v120, vcc, 0x1000, v128
	s_waitcnt lgkmcnt(0)
	v_mul_f32_e32 v16, v16, v125
	v_fmac_f32_e32 v17, v121, v125
	v_addc_co_u32_e32 v121, vcc, 0, v129, vcc
	global_store_dwordx2 v[120:121], v[16:17], off sc1
	s_branch .LBB0_425
